# grid barrier: waiters poll the global generation word directly instead of waiting for their XCD leader's relay
# speedup vs baseline: 1.0462x; 1.0028x over previous
.LBB0_227:
	s_or_b64 exec, exec, s[8:9]
	v_cvt_f32_u32_e32 v4, v2
	s_waitcnt vmcnt(0)
	v_readfirstlane_b32 s2, v3
	v_sub_u32_e32 v3, 0, v2
	v_rcp_iflag_f32_e32 v4, v4
	v_add_u32_e32 v5, s2, v1
	v_mul_f32_e32 v4, 0x4f7ffffe, v4
	v_cvt_u32_f32_e32 v4, v4
	v_mul_lo_u32 v1, v3, v4
	v_mul_hi_u32 v1, v4, v1
	v_add_u32_e32 v1, v4, v1
	v_mul_hi_u32 v1, v5, v1
	v_mul_lo_u32 v3, v1, v2
	v_sub_u32_e32 v3, v5, v3
	v_add_u32_e32 v4, 1, v1
	v_cmp_ge_u32_e32 vcc, v3, v2
	s_nop 1
	v_cndmask_b32_e32 v1, v1, v4, vcc
	v_sub_u32_e32 v4, v3, v2
	v_cndmask_b32_e32 v3, v3, v4, vcc
	v_add_u32_e32 v4, 1, v1
	v_cmp_ge_u32_e32 vcc, v3, v2
	v_add_u32_e32 v3, 1, v5
	s_nop 0
	v_cndmask_b32_e32 v1, v1, v4, vcc
	v_mul_lo_u32 v4, v2, v1
	v_add_u32_e32 v2, v4, v2
	v_cmp_ne_u32_e32 vcc, v3, v2
	s_and_saveexec_b64 s[2:3], vcc
	s_xor_b64 s[2:3], exec, s[2:3]
	s_cbranch_execz .LBB0_241
	s_movk_i32 s8, 0xd40
	s_mov_b32 s9, 0
	s_lshl_b64 s[8:9], s[8:9], 2
	v_readlane_b32 s10, v252, 0
	v_readlane_b32 s11, v252, 1
	s_add_u32 s12, s10, s8
	s_addc_u32 s13, s11, s9
	v_mov_b32_e32 v0, 0
	global_load_dword v2, v0, s[12:13] sc1
	s_waitcnt vmcnt(0)
	v_cmp_eq_u32_e32 vcc, v2, v1
	s_and_saveexec_b64 s[8:9], vcc
	s_cbranch_execz .LBB0_240
	v_readlane_b32 s16, v252, 2
	v_readlane_b32 s18, v252, 4
	v_readlane_b32 s19, v252, 5
	s_add_u32 s10, s18, 0xf210200
	v_readlane_b32 s17, v252, 3
	s_addc_u32 s11, s19, 0
	s_mov_b32 s25, 1
	s_mov_b64 s[14:15], 0
	v_readlane_b32 s20, v252, 6
	v_readlane_b32 s21, v252, 7
	v_readlane_b32 s22, v252, 8
	v_readlane_b32 s23, v252, 9
	s_branch .LBB0_231

.LBB0_335:
	s_or_b64 exec, exec, s[8:9]
	v_cvt_f32_u32_e32 v4, v2
	s_waitcnt vmcnt(0)
	v_readfirstlane_b32 s2, v3
	v_sub_u32_e32 v3, 0, v2
	v_rcp_iflag_f32_e32 v4, v4
	v_add_u32_e32 v5, s2, v1
	v_mul_f32_e32 v4, 0x4f7ffffe, v4
	v_cvt_u32_f32_e32 v4, v4
	v_mul_lo_u32 v1, v3, v4
	v_mul_hi_u32 v1, v4, v1
	v_add_u32_e32 v1, v4, v1
	v_mul_hi_u32 v1, v5, v1
	v_mul_lo_u32 v3, v1, v2
	v_sub_u32_e32 v3, v5, v3
	v_add_u32_e32 v4, 1, v1
	v_cmp_ge_u32_e32 vcc, v3, v2
	s_nop 1
	v_cndmask_b32_e32 v1, v1, v4, vcc
	v_sub_u32_e32 v4, v3, v2
	v_cndmask_b32_e32 v3, v3, v4, vcc
	v_add_u32_e32 v4, 1, v1
	v_cmp_ge_u32_e32 vcc, v3, v2
	v_add_u32_e32 v3, 1, v5
	s_nop 0
	v_cndmask_b32_e32 v1, v1, v4, vcc
	v_mul_lo_u32 v4, v2, v1
	v_add_u32_e32 v2, v4, v2
	v_cmp_ne_u32_e32 vcc, v3, v2
	s_and_saveexec_b64 s[2:3], vcc
	s_xor_b64 s[2:3], exec, s[2:3]
	s_cbranch_execz .LBB0_349
	s_mov_b64 s[10:11], 0x3e38aa3b
	s_movk_i32 s8, 0xd40
	s_mov_b32 s9, s11
	s_lshl_b64 s[8:9], s[8:9], 2
	v_readlane_b32 s10, v252, 0
	v_readlane_b32 s11, v252, 1
	s_add_u32 s10, s10, s8
	s_addc_u32 s11, s11, s9
	s_nop 2
	global_load_dword v0, v193, s[10:11] sc1
	s_waitcnt vmcnt(0)
	v_cmp_eq_u32_e32 vcc, v0, v1
	s_and_saveexec_b64 s[8:9], vcc
	s_cbranch_execz .LBB0_348
	s_mov_b32 s23, 1
	s_mov_b64 s[12:13], 0
	s_branch .LBB0_339
